# attention loop: default issue arbitration (s_setprio 1/0 pair around the QK MFMA cluster removed)
# speedup vs baseline: 1.0042x; 1.0042x over previous
; template <bool NA> ...
;     ...
;         if (active) {
;             const LAS unsigned char* kb = lds + cur * KB; const LAS unsigned char* vb = lds + VOFF + cur * VB;
;             f32x16 p0, p1;
;             if (NA) {
; #pragma unroll
;                 for (int r = 0; r < 16; ++r) { p0[r] = 0.f; p1[r] = 0.f; }
;             } else { p0 = negm; p1 = negm; }
;             bf16x8 kf[8], vfr[8];
; #pragma unroll
;             for (int s = 0; s < 4; ++s) {
;                 kf[2 * s] = *(const LAS bf16x8*)(kb + q * 144 + (16 * s + 8 * h) * 2);
;                 kf[2 * s + 1] = *(const LAS bf16x8*)(kb + (q + 32) * 144 + (16 * s + 8 * h) * 2);
;             }
; #pragma unroll
;             for (int s = 0; s < 4; ++s) {
;                 vfr[2 * s] = *(const LAS bf16x8*)(vb + q * 144 + 32 * s + 16 * h);
;                 vfr[2 * s + 1] = *(const LAS bf16x8*)(vb + (q + 32) * 144 + 32 * s + 16 * h);
;             }
;             __builtin_amdgcn_sched_barrier(0);
;             __builtin_amdgcn_s_setprio(1);
; #pragma unroll
;             for (int s = 0; s < 4; ++s) {
;                 p0 = __builtin_amdgcn_mfma_f32_32x32x16_bf16(kf[2 * s], qb[s], p0, 0, 0, 0);
;                 p1 = __builtin_amdgcn_mfma_f32_32x32x16_bf16(kf[2 * s + 1], qb[s], p1, 0, 0, 0);
;             }
;             __builtin_amdgcn_s_setprio(0);
;             if (NA) {
;                 if (j >= 4) {
;                     const int dr = kr - na_r + 7, qc = na_qc0 + q;
; #pragma unroll
;                     for (int r = 0; r < 16; ++r) {
;                         const int kc = 8 * (r >> 2) + 4 * h + (r & 3);
;                         const bool v0 = (kc >= na_cs) && (kc < na_cs + 16), v1 = (kc + 32 >= na_cs) && (kc + 32 < na_cs + 16);
;                         const int i0 = v0 ? dr * 31 + (kc - qc + 15) : 0, i1 = v1 ? dr * 31 + (kc + 32 - qc + 15) : 0;
;                         const float b0 = biasL[i0], b1 = biasL[i1];
;                         p0[r] = v0 ? p0[r] * qs + b0 - m : -INFINITY; p1[r] = v1 ? p1[r] * qs + b1 - m : -INFINITY;
;                     }
;                 } else {
; #pragma unroll
;                     for (int r = 0; r < 16; ++r) { p0[r] = p0[r] * qs - m; p1[r] = p1[r] * qs - m; }
;                 }
;             }
;             float mx = fmaxf(fmaxf(p0[0], p1[0]), p0[1]), mx2 = fmaxf(fmaxf(p1[1], p0[2]), p1[2]);
; #pragma unroll
.LBB0_307:
	s_and_b32 s20, s2, 1
	s_mul_i32 s22, s20, 0x2400
	v_add_u32_e32 v50, s22, v194
	ds_read_b128 v[66:69], v50
	ds_read_b128 v[144:147], v50 offset:32
	ds_read_b128 v[148:151], v50 offset:4608
	ds_read_b128 v[188:191], v50 offset:4640
	ds_read_b128 v[196:199], v50 offset:64
	ds_read_b128 v[218:221], v50 offset:96
	ds_read_b128 v[222:225], v50 offset:4672
	ds_read_b128 v[226:229], v50 offset:4704
	ds_read_b128 v[134:137], v50 offset:18432
	ds_read_b128 v[126:129], v50 offset:18464
	ds_read_b128 v[130:133], v50 offset:23040
	ds_read_b128 v[122:125], v50 offset:23072
	ds_read_b128 v[118:121], v50 offset:18496
	ds_read_b128 v[90:93], v50 offset:18528
	ds_read_b128 v[114:117], v50 offset:23104
	ds_read_b128 v[94:97], v50 offset:23136
	s_waitcnt lgkmcnt(14)
	v_mfma_f32_32x32x16_bf16 v[50:65], v[66:69], v[98:101], v[2:17]
	v_mfma_f32_32x32x16_bf16 v[50:65], v[144:147], v[102:105], v[50:65]
	s_waitcnt lgkmcnt(13)
	v_mfma_f32_32x32x16_bf16 v[66:81], v[148:151], v[98:101], v[2:17]
	s_waitcnt lgkmcnt(12)
	v_mfma_f32_32x32x16_bf16 v[66:81], v[188:191], v[102:105], v[66:81]
	s_waitcnt lgkmcnt(11)
	v_mfma_f32_32x32x16_bf16 v[50:65], v[196:199], v[106:109], v[50:65]
	s_waitcnt lgkmcnt(9)
	v_mfma_f32_32x32x16_bf16 v[66:81], v[222:225], v[106:109], v[66:81]
	v_mfma_f32_32x32x16_bf16 v[50:65], v[218:221], v[110:113], v[50:65]
	s_waitcnt lgkmcnt(8)
	v_mfma_f32_32x32x16_bf16 v[66:81], v[226:229], v[110:113], v[66:81]
	s_mov_b64 s[22:23], 0xd8000
	v_lshl_add_u64 v[138:139], v[138:139], 0, s[22:23]
	v_lshl_add_u64 v[140:141], v[140:141], 0, s[10:11]
	s_nop 7
	v_max3_f32 v143, v50, v66, v51
	v_max3_f32 v143, v143, v53, v69
	v_max3_f32 v143, v143, v55, v71
	v_max3_f32 v143, v143, v56, v72
	v_max3_f32 v144, v67, v52, v68
	v_max3_f32 v143, v143, v58, v74
	v_max3_f32 v144, v144, v54, v70
	v_max3_f32 v143, v143, v59, v75
	v_max3_f32 v144, v144, v57, v73
	v_max3_f32 v143, v143, v61, v77
	v_max3_f32 v144, v144, v60, v76
	v_max3_f32 v143, v143, v62, v78
	v_max3_f32 v144, v144, v63, v79
	v_max3_f32 v143, v143, v64, v80
	v_max_f32_e32 v145, v65, v81
	v_max3_f32 v143, v143, v144, v145
	v_mov_b32_e32 v144, v143
	s_nop 1
	v_permlane32_swap_b32_e32 v143, v144
	v_max_f32_e32 v143, v143, v144
	v_cmp_lt_f32_e32 vcc, 0, v143
	s_cbranch_vccz .LBB0_309
	s_nop 0
	v_cndmask_b32_e32 v4, 0, v143, vcc
	v_exp_f32_e64 v6, -v4
	v_add_f32_e32 v183, v183, v4
	v_xor_b32_e32 v2, 0x80000000, v183
	v_pk_add_f32 v[50:51], v[50:51], v[4:5] op_sel_hi:[1,0] neg_lo:[0,1] neg_hi:[0,1]
	v_pk_add_f32 v[66:67], v[66:67], v[4:5] op_sel_hi:[1,0] neg_lo:[0,1] neg_hi:[0,1]
	v_pk_add_f32 v[52:53], v[52:53], v[4:5] op_sel_hi:[1,0] neg_lo:[0,1] neg_hi:[0,1]
	v_pk_add_f32 v[68:69], v[68:69], v[4:5] op_sel_hi:[1,0] neg_lo:[0,1] neg_hi:[0,1]
	v_pk_add_f32 v[54:55], v[54:55], v[4:5] op_sel_hi:[1,0] neg_lo:[0,1] neg_hi:[0,1]
	v_pk_add_f32 v[70:71], v[70:71], v[4:5] op_sel_hi:[1,0] neg_lo:[0,1] neg_hi:[0,1]
	v_pk_add_f32 v[56:57], v[56:57], v[4:5] op_sel_hi:[1,0] neg_lo:[0,1] neg_hi:[0,1]
	v_pk_add_f32 v[72:73], v[72:73], v[4:5] op_sel_hi:[1,0] neg_lo:[0,1] neg_hi:[0,1]
	v_pk_add_f32 v[58:59], v[58:59], v[4:5] op_sel_hi:[1,0] neg_lo:[0,1] neg_hi:[0,1]
	v_pk_add_f32 v[74:75], v[74:75], v[4:5] op_sel_hi:[1,0] neg_lo:[0,1] neg_hi:[0,1]
	v_pk_add_f32 v[60:61], v[60:61], v[4:5] op_sel_hi:[1,0] neg_lo:[0,1] neg_hi:[0,1]
	v_pk_add_f32 v[76:77], v[76:77], v[4:5] op_sel_hi:[1,0] neg_lo:[0,1] neg_hi:[0,1]
	v_pk_add_f32 v[62:63], v[62:63], v[4:5] op_sel_hi:[1,0] neg_lo:[0,1] neg_hi:[0,1]
	v_pk_add_f32 v[78:79], v[78:79], v[4:5] op_sel_hi:[1,0] neg_lo:[0,1] neg_hi:[0,1]
	v_pk_mul_f32 v[48:49], v[48:49], v[6:7] op_sel_hi:[1,0]
	v_pk_mul_f32 v[46:47], v[46:47], v[6:7] op_sel_hi:[1,0]
	v_pk_mul_f32 v[44:45], v[44:45], v[6:7] op_sel_hi:[1,0]
	v_pk_mul_f32 v[42:43], v[42:43], v[6:7] op_sel_hi:[1,0]
	v_pk_mul_f32 v[40:41], v[40:41], v[6:7] op_sel_hi:[1,0]
	v_pk_mul_f32 v[38:39], v[38:39], v[6:7] op_sel_hi:[1,0]
	v_pk_mul_f32 v[36:37], v[36:37], v[6:7] op_sel_hi:[1,0]
	v_pk_mul_f32 v[34:35], v[34:35], v[6:7] op_sel_hi:[1,0]
	v_pk_mul_f32 v[32:33], v[32:33], v[6:7] op_sel_hi:[1,0]
	v_pk_mul_f32 v[30:31], v[30:31], v[6:7] op_sel_hi:[1,0]
	v_pk_mul_f32 v[28:29], v[28:29], v[6:7] op_sel_hi:[1,0]
	v_pk_mul_f32 v[26:27], v[26:27], v[6:7] op_sel_hi:[1,0]
	v_pk_mul_f32 v[24:25], v[24:25], v[6:7] op_sel_hi:[1,0]
	v_pk_mul_f32 v[22:23], v[22:23], v[6:7] op_sel_hi:[1,0]
	v_pk_mul_f32 v[20:21], v[20:21], v[6:7] op_sel_hi:[1,0]
	v_pk_mul_f32 v[18:19], v[18:19], v[6:7] op_sel_hi:[1,0]
	v_pk_add_f32 v[64:65], v[64:65], v[4:5] op_sel_hi:[1,0] neg_lo:[0,1] neg_hi:[0,1]
	v_pk_add_f32 v[80:81], v[80:81], v[4:5] op_sel_hi:[1,0] neg_lo:[0,1] neg_hi:[0,1]
	v_mul_f32_e32 v142, v142, v6
	v_mov_b32_e32 v3, v2
	v_mov_b32_e32 v4, v2
	v_mov_b32_e32 v5, v2
	v_mov_b32_e32 v6, v2
	v_mov_b32_e32 v7, v2
	v_mov_b32_e32 v8, v2
	v_mov_b32_e32 v9, v2
	v_mov_b32_e32 v10, v2
	v_mov_b32_e32 v11, v2
	v_mov_b32_e32 v12, v2
	v_mov_b32_e32 v13, v2
	v_mov_b32_e32 v14, v2
	v_mov_b32_e32 v15, v2
	v_mov_b32_e32 v16, v2
	v_mov_b32_e32 v17, v2
